# tile-loop exit: store-draining vmcnt(0) before the closing s_barrier dropped (trailing DMAs already retired by the epilogue's own waits), 8 GEMM instances
# speedup vs baseline: 1.0060x; 1.0060x over previous
; #define PG8_WAIT_V(n) asm volatile("s_waitcnt vmcnt(" #n ")" ::: "memory")
; #define PG8_BAR __builtin_amdgcn_s_barrier()
; template <class Epi, class Sched, bool ALIGN_EPI = false, bool SP2 = false>
; __device__ __forceinline__ void gemm_phase(PG8_LAS unsigned char* lds, const Gemm g, const Sched& S, const Epi& E) {
;     ...
;     PG8_WAIT_V(0);
;     if constexpr (!ALIGN_EPI) { if (wr == 0) PG8_BAR; }
;     PG8_BAR;
.LBB0_264:
	s_nop 0
	v_readlane_b32 s28, v255, 30
	v_readlane_b32 s29, v255, 31
	s_mov_b32 s35, 0x18000
	s_mov_b32 s72, 0xc000
	s_barrier

; #define PG8_WAIT_V(n) asm volatile("s_waitcnt vmcnt(" #n ")" ::: "memory")
; #define PG8_BAR __builtin_amdgcn_s_barrier()
; template <class Epi, class Sched, bool ALIGN_EPI = false, bool SP2 = false>
; __device__ __forceinline__ void gemm_phase(PG8_LAS unsigned char* lds, const Gemm g, const Sched& S, const Epi& E) {
;     ...
;     PG8_WAIT_V(0);
;     if constexpr (!ALIGN_EPI) { if (wr == 0) PG8_BAR; }
;     PG8_BAR;
.LBB0_565:
	v_readlane_b32 s52, v252, 0
	s_nop 0
	v_readlane_b32 s53, v252, 1
	v_readlane_b32 s54, v252, 2
	v_readlane_b32 s55, v252, 3
	v_readlane_b32 s56, v252, 4
	v_readlane_b32 s57, v252, 5
	v_readlane_b32 s58, v252, 6
	v_readlane_b32 s59, v252, 7
	v_readlane_b32 s96, v255, 27
	v_readlane_b32 s60, v252, 8
	v_readlane_b32 s61, v252, 9
	v_readlane_b32 s62, v252, 10
	v_readlane_b32 s63, v252, 11
	s_mov_b64 s[52:53], s[56:57]
	v_readlane_b32 s28, v255, 30
	v_readlane_b32 s97, v255, 28
	s_mov_b64 s[54:55], s[58:59]
	v_readlane_b32 s94, v255, 29
	v_readlane_b32 s29, v255, 31
	v_readlane_b32 s95, v255, 32
	s_mov_b32 s73, 0x10000
	s_mov_b32 s35, 0x18000
	s_mov_b32 s72, 0xc000
	s_barrier
	v_readlane_b32 s64, v252, 12
	v_readlane_b32 s65, v252, 13
	v_readlane_b32 s66, v252, 14
	v_readlane_b32 s67, v252, 15
	s_mov_b64 s[56:57], s[60:61]
	s_mov_b64 s[58:59], s[62:63]

; #define PG8_WAIT_V(n) asm volatile("s_waitcnt vmcnt(" #n ")" ::: "memory")
; #define PG8_BAR __builtin_amdgcn_s_barrier()
; template <class Epi, class Sched, bool ALIGN_EPI = false, bool SP2 = false>
; __device__ __forceinline__ void gemm_phase(PG8_LAS unsigned char* lds, const Gemm g, const Sched& S, const Epi& E) {
;     ...
;     PG8_WAIT_V(0);
;     if constexpr (!ALIGN_EPI) { if (wr == 0) PG8_BAR; }
;     PG8_BAR;
.LBB0_587:
	v_readlane_b32 s52, v252, 0
	s_nop 0
	v_readlane_b32 s53, v252, 1
	v_readlane_b32 s54, v252, 2
	v_readlane_b32 s55, v252, 3
	v_readlane_b32 s56, v252, 4
	v_readlane_b32 s57, v252, 5
	v_readlane_b32 s58, v252, 6
	v_readlane_b32 s59, v252, 7
	v_readlane_b32 s96, v255, 27
	v_readlane_b32 s60, v252, 8
	v_readlane_b32 s61, v252, 9
	v_readlane_b32 s62, v252, 10
	v_readlane_b32 s63, v252, 11
	s_mov_b64 s[52:53], s[56:57]
	v_readlane_b32 s28, v255, 30
	v_readlane_b32 s97, v255, 28
	s_mov_b64 s[54:55], s[58:59]
	v_readlane_b32 s94, v255, 29
	v_readlane_b32 s29, v255, 31
	v_readlane_b32 s95, v255, 32
	s_mov_b32 s35, 0x18000
	s_mov_b32 s72, 0xc000
	s_barrier
	v_readlane_b32 s64, v252, 12
	v_readlane_b32 s65, v252, 13
	v_readlane_b32 s66, v252, 14
	v_readlane_b32 s67, v252, 15
	s_mov_b64 s[56:57], s[60:61]
	s_mov_b64 s[58:59], s[62:63]

; #define PG8_WAIT_V(n) asm volatile("s_waitcnt vmcnt(" #n ")" ::: "memory")
; #define PG8_BAR __builtin_amdgcn_s_barrier()
; template <class Epi, class Sched, bool ALIGN_EPI = false, bool SP2 = false>
; __device__ __forceinline__ void gemm_phase(PG8_LAS unsigned char* lds, const Gemm g, const Sched& S, const Epi& E) {
;     ...
;     PG8_WAIT_V(0);
;     if constexpr (!ALIGN_EPI) { if (wr == 0) PG8_BAR; }
;     PG8_BAR;
.LBB0_682:
	s_nop 0
	v_readlane_b32 s28, v255, 30
	v_readlane_b32 s29, v255, 31
	s_barrier

; #define PG8_WAIT_V(n) asm volatile("s_waitcnt vmcnt(" #n ")" ::: "memory")
; #define PG8_BAR __builtin_amdgcn_s_barrier()
; template <class Epi, class Sched, bool ALIGN_EPI = false, bool SP2 = false>
; __device__ __forceinline__ void gemm_phase(PG8_LAS unsigned char* lds, const Gemm g, const Sched& S, const Epi& E) {
;     ...
;     PG8_WAIT_V(0);
;     if constexpr (!ALIGN_EPI) { if (wr == 0) PG8_BAR; }
;     PG8_BAR;
.LBB0_796:
	s_nop 0
	v_readlane_b32 s28, v255, 30
	v_readlane_b32 s29, v255, 31
	s_mov_b32 s73, 0x10000
	s_mov_b32 s35, 0x18000
	s_mov_b32 s72, 0xc000
	s_barrier

; #define PG8_WAIT_V(n) asm volatile("s_waitcnt vmcnt(" #n ")" ::: "memory")
; #define PG8_BAR __builtin_amdgcn_s_barrier()
; template <class Epi, class Sched, bool ALIGN_EPI = false, bool SP2 = false>
; __device__ __forceinline__ void gemm_phase(PG8_LAS unsigned char* lds, const Gemm g, const Sched& S, const Epi& E) {
;     ...
;     PG8_WAIT_V(0);
;     if constexpr (!ALIGN_EPI) { if (wr == 0) PG8_BAR; }
;     PG8_BAR;
.LBB0_1028:
	s_nop 0
	v_readlane_b32 s28, v255, 30
	v_readlane_b32 s94, v255, 29
	v_readlane_b32 s29, v255, 31
	v_readlane_b32 s95, v255, 32
	s_mov_b32 s73, 0x10000
	s_mov_b32 s35, 0x18000
	s_mov_b32 s72, 0xc000
	s_barrier
